# transpose tile split K=4 (low CUs 4 tiles, high CUs rest) + P4 K-skip
# baseline (speedup 1.0000x reference)
.LBB0_87:
	s_load_dwordx16 s[4:19], s[0:1], 0xc0
	s_cmpk_gt_i32 s54, 0x17ff
	s_waitcnt lgkmcnt(0)
	v_writelane_b32 v253, s4, 12
	s_nop 1
	v_writelane_b32 v253, s5, 13
	v_writelane_b32 v253, s6, 14
	v_writelane_b32 v253, s7, 15
	v_writelane_b32 v253, s8, 16
	v_writelane_b32 v253, s9, 17
	v_writelane_b32 v253, s10, 18
	v_writelane_b32 v253, s11, 19
	v_writelane_b32 v253, s12, 20
	v_writelane_b32 v253, s13, 21
	v_writelane_b32 v253, s14, 22
	v_writelane_b32 v253, s15, 23
	v_writelane_b32 v253, s16, 24
	v_writelane_b32 v253, s17, 25
	v_writelane_b32 v253, s18, 26
	v_writelane_b32 v253, s19, 27
	s_cbranch_scc1 .LBB0_143
	s_load_dwordx2 s[4:5], s[0:1], 0x40
	s_load_dwordx2 s[6:7], s[0:1], 0xe8
	s_load_dwordx4 s[8:11], s[0:1], 0xf0
	s_load_dwordx2 s[12:13], s[0:1], 0x110
	s_movk_i32 s15, 0x70
	s_add_i32 s14, s54, 432
	s_movk_i32 s16, 0x17ff
	s_cmp_lt_u32 s54, 0x90
	s_cbranch_scc0 .Ltr_hi
	s_movk_i32 s15, 0x90
	s_mov_b32 s14, s54
	s_movk_i32 s16, 575
